# norm row loops: modulation vector loads of all four chunks hoisted, counted waits
# speedup vs baseline: 1.1375x; 1.0274x over previous
; __device__ __forceinline__ void st_bf4(bf16_t* p, const f32x4 v) { u32x2 w; w.x = cvt_pk_bf16(v[0], v[1]); w.y = cvt_pk_bf16(v[2], v[3]); *(u32x2*)p = w; }
; DI void norm_phase(const float* xp, const float* xs, const float* gvec, const float* MODL  , int sc_off, bf16_t* H, int tid,
;                    const float* P, int nparts, const float* pgate, float* X) {
;     ...
;         for (int j = 0; j < 4; ++j) ss += v[j][0] * v[j][0] + v[j][1] * v[j][1] + v[j][2] * v[j][2] + v[j][3] * v[j][3];
;         const float r = rsqrtf(wave_sum(ss, lane) * (1.f / 1024.f) + 1e-6f);
;         if (H) {
; #pragma unroll
;             for (int j = 0; j < 4; ++j) { const int c = 4 * lane + 256 * j; const f32x4 g = *(const f32x4*)(gvec + c), sh = *(const f32x4*)(mr + c), sc = *(const f32x4*)(mr + sc_off + c);
;                 st_bf4(H + (size_t)row * 1024 + c, v[j] * r * g * (1.f + sc) + sh); }
;         } else {
; #pragma unroll
;             for (int j = 0; j < 4; ++j) { const int c = 4 * lane + 256 * j; *(f32x4*)(X + (size_t)row * 1024 + c) = v[j] * r * *(const f32x4*)(gvec + c); }
;         }
.LBB0_16:
	s_or_b64 exec, exec, s[6:7]
	s_waitcnt vmcnt(0)
	v_pk_mul_f32 v[40:41], v[12:13], v[12:13]
	s_waitcnt vmcnt(2)
	v_pk_mul_f32 v[42:43], v[8:9], v[8:9]
	v_pk_mul_f32 v[36:37], v[14:15], v[14:15]
	v_pk_mul_f32 v[38:39], v[10:11], v[10:11]
	v_mov_b32_e32 v44, v40
	v_mov_b32_e32 v45, v42
	v_mov_b32_e32 v42, v41
	v_pk_add_f32 v[40:41], v[44:45], v[42:43]
	v_mov_b32_e32 v42, v36
	v_mov_b32_e32 v43, v38
	s_waitcnt vmcnt(0)
	v_pk_mul_f32 v[32:33], v[0:1], v[0:1]
	v_pk_mul_f32 v[34:35], v[4:5], v[4:5]
	v_pk_add_f32 v[40:41], v[42:43], v[40:41]
	v_mov_b32_e32 v38, v37
	v_pk_mul_f32 v[16:17], v[2:3], v[2:3]
	v_pk_mul_f32 v[18:19], v[6:7], v[6:7]
	v_pk_add_f32 v[36:37], v[38:39], v[40:41]
	v_mov_b32_e32 v38, v32
	v_mov_b32_e32 v39, v34
	v_mov_b32_e32 v34, v33
	v_pk_add_f32 v[32:33], v[38:39], v[34:35]
	v_mov_b32_e32 v34, v16
	v_mov_b32_e32 v35, v18
	v_pk_add_f32 v[32:33], v[34:35], v[32:33]
	v_mov_b32_e32 v18, v17
	v_pk_add_f32 v[16:17], v[18:19], v[32:33]
	global_load_dwordx4 v[32:35], v[28:29], off
	global_load_dwordx4 v[198:201], v[28:29], off offset:1024
	global_load_dwordx4 v[202:205], v[28:29], off offset:2048
	global_load_dwordx4 v[206:209], v[28:29], off offset:3072
	v_add_f32_e32 v18, v36, v37
	v_add_f32_e32 v17, v17, v18
	v_add_f32_e32 v16, v16, v17
	ds_bpermute_b32 v17, v50, v16
	v_lshl_add_u64 v[20:21], v[20:21], 0, s[48:49]
	s_movk_i32 s6, 0x41ff
	s_waitcnt lgkmcnt(0)
	v_add_f32_e32 v16, v16, v17
	ds_bpermute_b32 v17, v51, v16
	s_waitcnt lgkmcnt(0)
	v_add_f32_e32 v16, v16, v17
	ds_bpermute_b32 v17, v52, v16
	s_waitcnt lgkmcnt(0)
	v_add_f32_e32 v16, v16, v17
	ds_bpermute_b32 v17, v53, v16
	s_waitcnt lgkmcnt(0)
	v_add_f32_e32 v16, v16, v17
	ds_bpermute_b32 v17, v54, v16
	s_waitcnt lgkmcnt(0)
	v_add_f32_e32 v16, v16, v17
	ds_bpermute_b32 v17, v55, v16
	s_waitcnt lgkmcnt(0)
	v_add_f32_e32 v16, v16, v17
	v_mov_b32_e32 v17, 0x358637bd
	v_fmamk_f32 v16, v16, 0x3a800000, v17
	v_cmp_gt_f32_e32 vcc, s42, v16
	v_mul_f32_e32 v17, 0x4b800000, v16
	s_nop 0
	v_cndmask_b32_e32 v16, v16, v17, vcc
	v_rsq_f32_e32 v16, v16
	s_nop 0
	v_mul_f32_e32 v17, 0x45800000, v16
	v_cndmask_b32_e32 v16, v16, v17, vcc
	v_pk_mul_f32 v[12:13], v[12:13], v[16:17] op_sel_hi:[1,0]
	v_pk_mul_f32 v[14:15], v[14:15], v[16:17] op_sel_hi:[1,0]
	v_cmp_lt_i32_e32 vcc, s6, v20
	s_or_b64 s[4:5], vcc, s[4:5]
	s_waitcnt vmcnt(3)
	v_pk_mul_f32 v[14:15], v[34:35], v[14:15]
	v_pk_mul_f32 v[12:13], v[32:33], v[12:13]
	global_store_dwordx4 v[30:31], v[12:15], off
	v_pk_mul_f32 v[8:9], v[8:9], v[16:17] op_sel_hi:[1,0]
	v_pk_mul_f32 v[10:11], v[10:11], v[16:17] op_sel_hi:[1,0]
	s_waitcnt vmcnt(3)
	v_pk_mul_f32 v[8:9], v[198:199], v[8:9]
	v_pk_mul_f32 v[10:11], v[200:201], v[10:11]
	global_store_dwordx4 v[30:31], v[8:11], off offset:1024
	v_pk_mul_f32 v[4:5], v[4:5], v[16:17] op_sel_hi:[1,0]
	v_pk_mul_f32 v[6:7], v[6:7], v[16:17] op_sel_hi:[1,0]
	s_waitcnt vmcnt(3)
	v_pk_mul_f32 v[4:5], v[202:203], v[4:5]
	v_pk_mul_f32 v[6:7], v[204:205], v[6:7]
	global_store_dwordx4 v[30:31], v[4:7], off offset:2048
	v_pk_mul_f32 v[0:1], v[0:1], v[16:17] op_sel_hi:[1,0]
	v_pk_mul_f32 v[2:3], v[2:3], v[16:17] op_sel_hi:[1,0]
	s_waitcnt vmcnt(3)
	v_pk_mul_f32 v[0:1], v[206:207], v[0:1]
	v_pk_mul_f32 v[2:3], v[208:209], v[2:3]
	global_store_dwordx4 v[30:31], v[0:3], off offset:3072
	s_andn2_b64 exec, exec, s[4:5]
	s_cbranch_execz .LBB0_130

; __device__ __forceinline__ void st_bf4(bf16_t* p, const f32x4 v) { u32x2 w; w.x = cvt_pk_bf16(v[0], v[1]); w.y = cvt_pk_bf16(v[2], v[3]); *(u32x2*)p = w; }
; DI void norm_phase(const float* xp, const float* xs, const float* gvec, const float* MODL  , int sc_off, bf16_t* H, int tid,
;                    const float* P, int nparts, const float* pgate, float* X) {
;     ...
;         for (int j = 0; j < 4; ++j) ss += v[j][0] * v[j][0] + v[j][1] * v[j][1] + v[j][2] * v[j][2] + v[j][3] * v[j][3];
;         const float r = rsqrtf(wave_sum(ss, lane) * (1.f / 1024.f) + 1e-6f);
;         if (H) {
; #pragma unroll
;             for (int j = 0; j < 4; ++j) { const int c = 4 * lane + 256 * j; const f32x4 g = *(const f32x4*)(gvec + c), sh = *(const f32x4*)(mr + c), sc = *(const f32x4*)(mr + sc_off + c);
;                 st_bf4(H + (size_t)row * 1024 + c, v[j] * r * g * (1.f + sc) + sh); }
.LBB0_227:
	s_or_b64 exec, exec, s[6:7]
	s_waitcnt vmcnt(0)
	v_pk_mul_f32 v[50:51], v[12:13], v[12:13]
	v_pk_mul_f32 v[52:53], v[8:9], v[8:9]
	v_pk_mul_f32 v[46:47], v[14:15], v[14:15]
	v_pk_mul_f32 v[48:49], v[10:11], v[10:11]
	v_mov_b32_e32 v60, v50
	v_mov_b32_e32 v61, v52
	v_mov_b32_e32 v52, v51
	v_pk_add_f32 v[50:51], v[60:61], v[52:53]
	v_mov_b32_e32 v52, v46
	v_mov_b32_e32 v53, v48
	v_pk_mul_f32 v[42:43], v[0:1], v[0:1]
	v_pk_mul_f32 v[44:45], v[4:5], v[4:5]
	v_pk_add_f32 v[50:51], v[52:53], v[50:51]
	v_mov_b32_e32 v48, v47
	v_lshl_add_u64 v[40:41], v[36:37], 2, s[4:5]
	v_pk_mul_f32 v[36:37], v[2:3], v[2:3]
	v_pk_mul_f32 v[38:39], v[6:7], v[6:7]
	v_pk_add_f32 v[46:47], v[48:49], v[50:51]
	v_mov_b32_e32 v48, v42
	v_mov_b32_e32 v49, v44
	v_mov_b32_e32 v44, v43
	v_pk_add_f32 v[42:43], v[48:49], v[44:45]
	v_mov_b32_e32 v44, v36
	v_mov_b32_e32 v45, v38
	v_pk_add_f32 v[42:43], v[44:45], v[42:43]
	v_mov_b32_e32 v38, v37
	s_mov_b64 s[6:7], 0x1000
	v_pk_add_f32 v[36:37], v[38:39], v[42:43]
	v_lshl_add_u64 v[38:39], v[40:41], 0, s[6:7]
	v_lshl_add_u64 v[40:41], v[40:41], 0, v[96:97]
	v_lshl_add_u64 v[50:51], v[38:39], 0, v[96:97]
	v_add_f32_e32 v29, v46, v47
	global_load_dwordx4 v[42:45], v[24:25], off
	global_load_dwordx4 v[46:49], v[40:41], off
	v_add_f32_e32 v29, v37, v29
	global_load_dwordx4 v[50:53], v[50:51], off
	global_load_dwordx4 v[198:201], v[24:25], off offset:1024
	global_load_dwordx4 v[210:213], v[40:41], off offset:1024
	v_mov_b32_e32 v234, v28
	v_mov_b32_e32 v235, v97
	v_lshl_add_u64 v[234:235], v[38:39], 0, v[234:235]
	global_load_dwordx4 v[222:225], v[234:235], off
	global_load_dwordx4 v[202:205], v[24:25], off offset:2048
	global_load_dwordx4 v[214:217], v[40:41], off offset:2048
	v_mov_b32_e32 v236, v30
	v_mov_b32_e32 v237, v97
	v_lshl_add_u64 v[236:237], v[38:39], 0, v[236:237]
	global_load_dwordx4 v[226:229], v[236:237], off
	global_load_dwordx4 v[206:209], v[24:25], off offset:3072
	global_load_dwordx4 v[218:221], v[40:41], off offset:3072
	v_mov_b32_e32 v238, v32
	v_mov_b32_e32 v239, v97
	v_lshl_add_u64 v[238:239], v[38:39], 0, v[238:239]
	global_load_dwordx4 v[230:233], v[238:239], off
	v_add_f32_e32 v29, v36, v29
	ds_bpermute_b32 v31, v54, v29
	v_lshl_add_u64 v[34:35], v[34:35], 1, v[26:27]
	v_mov_b32_e32 v33, v97
	v_lshl_add_u64 v[16:17], v[16:17], 0, s[48:49]
	s_movk_i32 s6, 0x41ff
	s_waitcnt lgkmcnt(0)
	v_add_f32_e32 v29, v29, v31
	ds_bpermute_b32 v31, v55, v29
	s_waitcnt lgkmcnt(0)
	v_add_f32_e32 v29, v29, v31
	ds_bpermute_b32 v31, v56, v29
	s_waitcnt lgkmcnt(0)
	v_add_f32_e32 v29, v29, v31
	ds_bpermute_b32 v31, v57, v29
	s_waitcnt lgkmcnt(0)
	v_add_f32_e32 v29, v29, v31
	ds_bpermute_b32 v31, v58, v29
	s_waitcnt lgkmcnt(0)
	v_add_f32_e32 v29, v29, v31
	ds_bpermute_b32 v31, v59, v29
	s_waitcnt lgkmcnt(0)
	v_add_f32_e32 v29, v29, v31
	v_mov_b32_e32 v31, 0x358637bd
	v_fmamk_f32 v29, v29, 0x3a800000, v31
	v_cmp_gt_f32_e32 vcc, s42, v29
	v_mul_f32_e32 v31, 0x4b800000, v29
	s_nop 0
	v_cndmask_b32_e32 v29, v29, v31, vcc
	v_rsq_f32_e32 v29, v29
	s_nop 0
	v_mul_f32_e32 v31, 0x45800000, v29
	v_cndmask_b32_e32 v36, v29, v31, vcc
	v_pk_mul_f32 v[14:15], v[14:15], v[36:37] op_sel_hi:[1,0]
	v_pk_mul_f32 v[12:13], v[12:13], v[36:37] op_sel_hi:[1,0]
	v_mov_b32_e32 v29, v97
	v_pk_mul_f32 v[10:11], v[10:11], v[36:37] op_sel_hi:[1,0]
	v_pk_mul_f32 v[8:9], v[8:9], v[36:37] op_sel_hi:[1,0]
	v_mov_b32_e32 v31, v97
	v_pk_mul_f32 v[6:7], v[6:7], v[36:37] op_sel_hi:[1,0]
	v_pk_mul_f32 v[4:5], v[4:5], v[36:37] op_sel_hi:[1,0]
	v_pk_mul_f32 v[2:3], v[2:3], v[36:37] op_sel_hi:[1,0]
	v_pk_mul_f32 v[0:1], v[0:1], v[36:37] op_sel_hi:[1,0]
	v_cmp_lt_i32_e32 vcc, s6, v16
	s_or_b64 s[8:9], vcc, s[8:9]
	s_waitcnt vmcnt(9)
	v_pk_mul_f32 v[12:13], v[42:43], v[12:13]
	v_pk_mul_f32 v[14:15], v[44:45], v[14:15]
	v_pk_add_f32 v[50:51], v[50:51], 1.0 op_sel_hi:[1,0]
	v_pk_add_f32 v[52:53], v[52:53], 1.0 op_sel_hi:[1,0]
	v_pk_fma_f32 v[12:13], v[50:51], v[12:13], v[46:47]
	v_pk_fma_f32 v[14:15], v[52:53], v[14:15], v[48:49]
	v_cvt_pk_bf16_f32 v12, v12, v13
	v_cvt_pk_bf16_f32 v13, v14, v15
	global_store_dwordx2 v[34:35], v[12:13], off
	s_waitcnt vmcnt(7)
	v_pk_mul_f32 v[8:9], v[198:199], v[8:9]
	v_pk_mul_f32 v[10:11], v[200:201], v[10:11]
	v_pk_add_f32 v[222:223], v[222:223], 1.0 op_sel_hi:[1,0]
	v_pk_add_f32 v[224:225], v[224:225], 1.0 op_sel_hi:[1,0]
	v_pk_fma_f32 v[8:9], v[222:223], v[8:9], v[210:211]
	v_pk_fma_f32 v[10:11], v[224:225], v[10:11], v[212:213]
	v_cvt_pk_bf16_f32 v8, v8, v9
	v_cvt_pk_bf16_f32 v9, v10, v11
	global_store_dwordx2 v[34:35], v[8:9], off offset:512
	s_waitcnt vmcnt(5)
	v_pk_mul_f32 v[4:5], v[202:203], v[4:5]
	v_pk_mul_f32 v[6:7], v[204:205], v[6:7]
	v_pk_add_f32 v[226:227], v[226:227], 1.0 op_sel_hi:[1,0]
	v_pk_add_f32 v[228:229], v[228:229], 1.0 op_sel_hi:[1,0]
	v_pk_fma_f32 v[4:5], v[226:227], v[4:5], v[214:215]
	v_pk_fma_f32 v[6:7], v[228:229], v[6:7], v[216:217]
	v_cvt_pk_bf16_f32 v4, v4, v5
	v_cvt_pk_bf16_f32 v5, v6, v7
	global_store_dwordx2 v[34:35], v[4:5], off offset:1024
	s_waitcnt vmcnt(3)
	v_pk_mul_f32 v[0:1], v[206:207], v[0:1]
	v_pk_mul_f32 v[2:3], v[208:209], v[2:3]
	v_pk_add_f32 v[230:231], v[230:231], 1.0 op_sel_hi:[1,0]
	v_pk_add_f32 v[232:233], v[232:233], 1.0 op_sel_hi:[1,0]
	v_pk_fma_f32 v[0:1], v[230:231], v[0:1], v[218:219]
	v_pk_fma_f32 v[2:3], v[232:233], v[2:3], v[220:221]
	v_cvt_pk_bf16_f32 v0, v0, v1
	v_cvt_pk_bf16_f32 v1, v2, v3
	global_store_dwordx2 v[34:35], v[0:1], off offset:1536
	s_andn2_b64 exec, exec, s[8:9]
	s_cbranch_execz .LBB0_230

; __device__ __forceinline__ void st_bf4(bf16_t* p, const f32x4 v) { u32x2 w; w.x = cvt_pk_bf16(v[0], v[1]); w.y = cvt_pk_bf16(v[2], v[3]); *(u32x2*)p = w; }
; DI void norm_phase(const float* xp, const float* xs, const float* gvec, const float* MODL  , int sc_off, bf16_t* H, int tid,
;                    const float* P, int nparts, const float* pgate, float* X) {
;     ...
;         for (int j = 0; j < 4; ++j) ss += v[j][0] * v[j][0] + v[j][1] * v[j][1] + v[j][2] * v[j][2] + v[j][3] * v[j][3];
;         const float r = rsqrtf(wave_sum(ss, lane) * (1.f / 1024.f) + 1e-6f);
;         if (H) {
; #pragma unroll
;             for (int j = 0; j < 4; ++j) { const int c = 4 * lane + 256 * j; const f32x4 g = *(const f32x4*)(gvec + c), sh = *(const f32x4*)(mr + c), sc = *(const f32x4*)(mr + sc_off + c);
;                 st_bf4(H + (size_t)row * 1024 + c, v[j] * r * g * (1.f + sc) + sh); }
.LBB0_1952:
	s_or_b64 exec, exec, s[6:7]
	s_waitcnt vmcnt(0)
	v_pk_mul_f32 v[50:51], v[12:13], v[12:13]
	v_pk_mul_f32 v[52:53], v[8:9], v[8:9]
	v_pk_mul_f32 v[46:47], v[14:15], v[14:15]
	v_pk_mul_f32 v[48:49], v[10:11], v[10:11]
	v_mov_b32_e32 v54, v50
	v_mov_b32_e32 v55, v52
	v_mov_b32_e32 v52, v51
	v_pk_add_f32 v[50:51], v[54:55], v[52:53]
	v_mov_b32_e32 v52, v46
	v_mov_b32_e32 v53, v48
	v_pk_mul_f32 v[42:43], v[0:1], v[0:1]
	v_pk_mul_f32 v[44:45], v[4:5], v[4:5]
	v_pk_add_f32 v[50:51], v[52:53], v[50:51]
	v_mov_b32_e32 v48, v47
	v_pk_mul_f32 v[16:17], v[2:3], v[2:3]
	v_pk_mul_f32 v[18:19], v[6:7], v[6:7]
	v_pk_add_f32 v[46:47], v[48:49], v[50:51]
	v_mov_b32_e32 v48, v42
	v_mov_b32_e32 v49, v44
	v_mov_b32_e32 v44, v43
	v_pk_add_f32 v[42:43], v[48:49], v[44:45]
	v_mov_b32_e32 v44, v16
	v_mov_b32_e32 v45, v18
	v_pk_add_f32 v[42:43], v[44:45], v[42:43]
	v_mov_b32_e32 v18, v17
	v_lshl_add_u64 v[40:41], v[40:41], 2, s[2:3]
	v_pk_add_f32 v[16:17], v[18:19], v[42:43]
	v_add_f32_e32 v18, v46, v47
	s_mov_b64 s[6:7], 0x1000
	v_add_f32_e32 v17, v17, v18
	v_lshl_add_u64 v[18:19], v[40:41], 0, s[6:7]
	v_lshl_add_u64 v[40:41], v[40:41], 0, v[96:97]
	v_lshl_add_u64 v[50:51], v[18:19], 0, v[96:97]
	global_load_dwordx4 v[42:45], v[28:29], off
	global_load_dwordx4 v[46:49], v[40:41], off
	v_add_f32_e32 v16, v16, v17
	global_load_dwordx4 v[50:53], v[50:51], off
	global_load_dwordx4 v[198:201], v[28:29], off offset:1024
	global_load_dwordx4 v[210:213], v[40:41], off offset:1024
	v_mov_b32_e32 v234, v32
	v_mov_b32_e32 v235, v97
	v_lshl_add_u64 v[234:235], v[18:19], 0, v[234:235]
	global_load_dwordx4 v[222:225], v[234:235], off
	global_load_dwordx4 v[202:205], v[28:29], off offset:2048
	global_load_dwordx4 v[214:217], v[40:41], off offset:2048
	v_mov_b32_e32 v236, v34
	v_mov_b32_e32 v237, v97
	v_lshl_add_u64 v[236:237], v[18:19], 0, v[236:237]
	global_load_dwordx4 v[226:229], v[236:237], off
	global_load_dwordx4 v[206:209], v[28:29], off offset:3072
	global_load_dwordx4 v[218:221], v[40:41], off offset:3072
	v_mov_b32_e32 v238, v36
	v_mov_b32_e32 v239, v97
	v_lshl_add_u64 v[238:239], v[18:19], 0, v[238:239]
	global_load_dwordx4 v[230:233], v[238:239], off
	ds_bpermute_b32 v17, v62, v16
	v_lshl_add_u64 v[38:39], v[38:39], 1, v[30:31]
	v_mov_b32_e32 v33, v97
	v_mov_b32_e32 v35, v97
	v_mov_b32_e32 v37, v97
	s_waitcnt lgkmcnt(0)
	v_add_f32_e32 v16, v16, v17
	ds_bpermute_b32 v17, v63, v16
	v_lshl_add_u64 v[20:21], v[20:21], 0, s[48:49]
	s_movk_i32 s6, 0x41ff
	s_waitcnt lgkmcnt(0)
	v_add_f32_e32 v16, v16, v17
	ds_bpermute_b32 v17, v64, v16
	s_waitcnt lgkmcnt(0)
	v_add_f32_e32 v16, v16, v17
	ds_bpermute_b32 v17, v65, v16
	s_waitcnt lgkmcnt(0)
	v_add_f32_e32 v16, v16, v17
	ds_bpermute_b32 v17, v66, v16
	s_waitcnt lgkmcnt(0)
	v_add_f32_e32 v16, v16, v17
	ds_bpermute_b32 v17, v67, v16
	s_waitcnt lgkmcnt(0)
	v_add_f32_e32 v16, v16, v17
	v_mov_b32_e32 v17, 0x358637bd
	v_fmamk_f32 v16, v16, 0x3a800000, v17
	v_cmp_gt_f32_e32 vcc, s42, v16
	v_mul_f32_e32 v17, 0x4b800000, v16
	s_nop 0
	v_cndmask_b32_e32 v16, v16, v17, vcc
	v_rsq_f32_e32 v16, v16
	s_nop 0
	v_mul_f32_e32 v17, 0x45800000, v16
	v_cndmask_b32_e32 v16, v16, v17, vcc
	v_pk_mul_f32 v[14:15], v[14:15], v[16:17] op_sel_hi:[1,0]
	v_pk_mul_f32 v[12:13], v[12:13], v[16:17] op_sel_hi:[1,0]
	v_pk_mul_f32 v[10:11], v[10:11], v[16:17] op_sel_hi:[1,0]
	v_pk_mul_f32 v[8:9], v[8:9], v[16:17] op_sel_hi:[1,0]
	v_pk_mul_f32 v[6:7], v[6:7], v[16:17] op_sel_hi:[1,0]
	v_pk_mul_f32 v[4:5], v[4:5], v[16:17] op_sel_hi:[1,0]
	v_pk_mul_f32 v[2:3], v[2:3], v[16:17] op_sel_hi:[1,0]
	v_pk_mul_f32 v[0:1], v[0:1], v[16:17] op_sel_hi:[1,0]
	v_cmp_lt_i32_e32 vcc, s6, v20
	s_or_b64 s[4:5], vcc, s[4:5]
	s_waitcnt vmcnt(9)
	v_pk_mul_f32 v[12:13], v[42:43], v[12:13]
	v_pk_mul_f32 v[14:15], v[44:45], v[14:15]
	v_pk_add_f32 v[50:51], v[50:51], 1.0 op_sel_hi:[1,0]
	v_pk_add_f32 v[52:53], v[52:53], 1.0 op_sel_hi:[1,0]
	v_pk_fma_f32 v[12:13], v[50:51], v[12:13], v[46:47]
	v_pk_fma_f32 v[14:15], v[52:53], v[14:15], v[48:49]
	v_cvt_pk_bf16_f32 v12, v12, v13
	v_cvt_pk_bf16_f32 v13, v14, v15
	global_store_dwordx2 v[38:39], v[12:13], off
	s_waitcnt vmcnt(7)
	v_pk_mul_f32 v[8:9], v[198:199], v[8:9]
	v_pk_mul_f32 v[10:11], v[200:201], v[10:11]
	v_pk_add_f32 v[222:223], v[222:223], 1.0 op_sel_hi:[1,0]
	v_pk_add_f32 v[224:225], v[224:225], 1.0 op_sel_hi:[1,0]
	v_pk_fma_f32 v[8:9], v[222:223], v[8:9], v[210:211]
	v_pk_fma_f32 v[10:11], v[224:225], v[10:11], v[212:213]
	v_cvt_pk_bf16_f32 v8, v8, v9
	v_cvt_pk_bf16_f32 v9, v10, v11
	global_store_dwordx2 v[38:39], v[8:9], off offset:512
	s_waitcnt vmcnt(5)
	v_pk_mul_f32 v[4:5], v[202:203], v[4:5]
	v_pk_mul_f32 v[6:7], v[204:205], v[6:7]
	v_pk_add_f32 v[226:227], v[226:227], 1.0 op_sel_hi:[1,0]
	v_pk_add_f32 v[228:229], v[228:229], 1.0 op_sel_hi:[1,0]
	v_pk_fma_f32 v[4:5], v[226:227], v[4:5], v[214:215]
	v_pk_fma_f32 v[6:7], v[228:229], v[6:7], v[216:217]
	v_cvt_pk_bf16_f32 v4, v4, v5
	v_cvt_pk_bf16_f32 v5, v6, v7
	global_store_dwordx2 v[38:39], v[4:5], off offset:1024
	s_waitcnt vmcnt(3)
	v_pk_mul_f32 v[0:1], v[206:207], v[0:1]
	v_pk_mul_f32 v[2:3], v[208:209], v[2:3]
	v_pk_add_f32 v[230:231], v[230:231], 1.0 op_sel_hi:[1,0]
	v_pk_add_f32 v[232:233], v[232:233], 1.0 op_sel_hi:[1,0]
	v_pk_fma_f32 v[0:1], v[230:231], v[0:1], v[218:219]
	v_pk_fma_f32 v[2:3], v[232:233], v[2:3], v[220:221]
	v_cvt_pk_bf16_f32 v0, v0, v1
	v_cvt_pk_bf16_f32 v1, v2, v3
	global_store_dwordx2 v[38:39], v[0:1], off offset:1536
	s_andn2_b64 exec, exec, s[4:5]
	s_cbranch_execz .LBB0_1955
